# setprio repair: s_setprio 0 moved from before to after the 8 attention QK^T MFMA clusters (priority raise now covers the cluster, as the PV clusters)
# baseline (speedup 1.0000x reference)
.LBB0_162:
	ds_read_b128 v[32:35], v115
	ds_read_b128 v[98:101], v115 offset:32
	ds_read_b128 v[36:39], v115 offset:4608
	ds_read_b128 v[102:105], v115 offset:4640
	ds_read_b128 v[106:109], v115 offset:64
	ds_read_b128 v[110:113], v115 offset:96
	ds_read_b128 v[122:125], v115 offset:4672
	ds_read_b128 v[126:129], v115 offset:4704
	s_setprio 1
	s_waitcnt lgkmcnt(7)
	v_mfma_f32_32x32x16_bf16 v[48:63], v[32:35], v[64:67], 0
	s_waitcnt lgkmcnt(5)
	v_mfma_f32_32x32x16_bf16 v[32:47], v[36:39], v[64:67], 0
	v_mfma_f32_32x32x16_bf16 v[48:63], v[98:101], v[68:71], v[48:63]
	s_waitcnt lgkmcnt(4)
	v_mfma_f32_32x32x16_bf16 v[32:47], v[102:105], v[68:71], v[32:47]
	s_waitcnt lgkmcnt(3)
	v_mfma_f32_32x32x16_bf16 v[48:63], v[106:109], v[72:75], v[48:63]
	s_waitcnt lgkmcnt(1)
	v_mfma_f32_32x32x16_bf16 v[32:47], v[122:125], v[72:75], v[32:47]
	v_mfma_f32_32x32x16_bf16 v[48:63], v[110:113], v[76:79], v[48:63]
	ds_read_b128 v[110:113], v119 offset:9216
	ds_read_b128 v[106:109], v119 offset:9248
	ds_read_b128 v[102:105], v119 offset:9280
	ds_read_b128 v[98:101], v119 offset:9312
	s_waitcnt lgkmcnt(4)
	v_mfma_f32_32x32x16_bf16 v[32:47], v[126:129], v[76:79], v[32:47]
	s_setprio 0
	s_nop 11
	v_max3_f32 v96, v32, v33, v34
	v_max3_f32 v96, v96, v35, v36
	v_max3_f32 v96, v96, v37, v38
	v_max3_f32 v96, v96, v39, v40
	v_max3_f32 v96, v96, v41, v42
	v_max3_f32 v96, v96, v43, v44
	v_max3_f32 v96, v96, v45, v46
	v_max3_f32 v96, v96, v47, v48
	v_max3_f32 v96, v96, v49, v50
	v_max3_f32 v96, v96, v51, v52
	v_max3_f32 v96, v96, v53, v54
	v_max3_f32 v96, v96, v55, v56
	v_max3_f32 v96, v96, v57, v58
	v_max3_f32 v96, v96, v59, v60
	v_max3_f32 v96, v96, v61, v62
	v_max_f32_e32 v96, v96, v63
	v_mov_b32_e32 v122, v96
	s_nop 1
	v_permlane32_swap_b32_e32 v96, v122
	v_max3_f32 v122, v120, v96, v122
	v_add_f32_e32 v96, 0x41000000, v120
	v_cmp_gt_f32_e32 vcc, v122, v96
	s_cbranch_vccz .LBB0_164
	v_sub_f32_e32 v96, v120, v122
	v_exp_f32_e32 v96, v96
	s_nop 0
	v_mul_f32_e32 v121, v121, v96
	v_pk_mul_f32 v[14:15], v[14:15], v[96:97] op_sel_hi:[1,0]
	v_pk_mul_f32 v[12:13], v[12:13], v[96:97] op_sel_hi:[1,0]
	v_pk_mul_f32 v[10:11], v[10:11], v[96:97] op_sel_hi:[1,0]
	v_pk_mul_f32 v[8:9], v[8:9], v[96:97] op_sel_hi:[1,0]
	v_pk_mul_f32 v[6:7], v[6:7], v[96:97] op_sel_hi:[1,0]
	v_pk_mul_f32 v[4:5], v[4:5], v[96:97] op_sel_hi:[1,0]
	v_pk_mul_f32 v[2:3], v[2:3], v[96:97] op_sel_hi:[1,0]
	v_pk_mul_f32 v[0:1], v[0:1], v[96:97] op_sel_hi:[1,0]
	v_pk_mul_f32 v[30:31], v[30:31], v[96:97] op_sel_hi:[1,0]
	v_pk_mul_f32 v[28:29], v[28:29], v[96:97] op_sel_hi:[1,0]
	v_pk_mul_f32 v[26:27], v[26:27], v[96:97] op_sel_hi:[1,0]
	v_pk_mul_f32 v[24:25], v[24:25], v[96:97] op_sel_hi:[1,0]
	v_pk_mul_f32 v[22:23], v[22:23], v[96:97] op_sel_hi:[1,0]
	v_pk_mul_f32 v[20:21], v[20:21], v[96:97] op_sel_hi:[1,0]
	v_pk_mul_f32 v[18:19], v[18:19], v[96:97] op_sel_hi:[1,0]
	v_pk_mul_f32 v[16:17], v[16:17], v[96:97] op_sel_hi:[1,0]
	s_branch .LBB0_165

.LBB0_167:
	v_add_f32_e32 v32, v48, v32
	v_add_f32_e32 v32, 0, v32
	v_add_f32_e32 v33, v49, v33
	v_add_f32_e32 v32, v33, v32
	v_add_f32_e32 v33, v50, v34
	v_add_f32_e32 v32, v33, v32
	v_add_f32_e32 v33, v51, v35
	v_add_f32_e32 v32, v33, v32
	v_add_f32_e32 v33, v52, v36
	v_add_f32_e32 v32, v33, v32
	v_add_f32_e32 v33, v53, v37
	v_add_f32_e32 v32, v33, v32
	v_add_f32_e32 v33, v54, v38
	v_add_f32_e32 v32, v33, v32
	v_add_f32_e32 v33, v55, v39
	v_add_f32_e32 v32, v33, v32
	v_add_f32_e32 v33, v56, v40
	v_add_f32_e32 v32, v33, v32
	v_add_f32_e32 v33, v57, v41
	v_add_f32_e32 v32, v33, v32
	v_add_f32_e32 v33, v58, v42
	v_add_f32_e32 v32, v33, v32
	v_add_f32_e32 v33, v59, v43
	v_add_f32_e32 v32, v33, v32
	v_add_f32_e32 v33, v60, v44
	v_add_f32_e32 v32, v33, v32
	v_add_f32_e32 v33, v61, v45
	v_add_f32_e32 v32, v33, v32
	v_add_f32_e32 v33, v62, v46
	v_add_f32_e32 v32, v33, v32
	v_add_f32_e32 v33, v63, v47
	v_add_f32_e32 v32, v33, v32
	v_add_f32_e32 v96, v121, v32
	ds_read_b128 v[32:35], v115 offset:23040
	ds_read_b128 v[36:39], v115 offset:18432
	ds_read_b128 v[98:101], v115 offset:18464
	ds_read_b128 v[102:105], v115 offset:23072
	ds_read_b128 v[106:109], v115 offset:18496
	ds_read_b128 v[110:113], v115 offset:23104
	ds_read_b128 v[124:127], v115 offset:18528
	ds_read_b128 v[128:131], v115 offset:23136
	s_setprio 1
	s_waitcnt lgkmcnt(6)
	v_mfma_f32_32x32x16_bf16 v[48:63], v[36:39], v[64:67], 0
	v_mfma_f32_32x32x16_bf16 v[32:47], v[32:35], v[64:67], 0
	s_waitcnt lgkmcnt(5)
	v_mfma_f32_32x32x16_bf16 v[48:63], v[98:101], v[68:71], v[48:63]
	s_waitcnt lgkmcnt(4)
	v_mfma_f32_32x32x16_bf16 v[32:47], v[102:105], v[68:71], v[32:47]
	s_waitcnt lgkmcnt(3)
	v_mfma_f32_32x32x16_bf16 v[48:63], v[106:109], v[72:75], v[48:63]
	s_waitcnt lgkmcnt(2)
	v_mfma_f32_32x32x16_bf16 v[32:47], v[110:113], v[72:75], v[32:47]
	ds_read_b128 v[110:113], v119 offset:27648
	ds_read_b128 v[106:109], v119 offset:27680
	ds_read_b128 v[102:105], v119 offset:27712
	ds_read_b128 v[98:101], v119 offset:27744
	s_waitcnt lgkmcnt(5)
	v_mfma_f32_32x32x16_bf16 v[48:63], v[124:127], v[76:79], v[48:63]
	s_waitcnt lgkmcnt(4)
	v_mfma_f32_32x32x16_bf16 v[32:47], v[128:131], v[76:79], v[32:47]
	s_setprio 0
	s_nop 11
	v_max3_f32 v120, v32, v33, v34
	v_max3_f32 v120, v120, v35, v36
	v_max3_f32 v120, v120, v37, v38
	v_max3_f32 v120, v120, v39, v40
	v_max3_f32 v120, v120, v41, v42
	v_max3_f32 v120, v120, v43, v44
	v_max3_f32 v120, v120, v45, v46
	v_max3_f32 v120, v120, v47, v48
	v_max3_f32 v120, v120, v49, v50
	v_max3_f32 v120, v120, v51, v52
	v_max3_f32 v120, v120, v53, v54
	v_max3_f32 v120, v120, v55, v56
	v_max3_f32 v120, v120, v57, v58
	v_max3_f32 v120, v120, v59, v60
	v_max3_f32 v120, v120, v61, v62
	v_max_f32_e32 v120, v120, v63
	v_mov_b32_e32 v121, v120
	s_nop 1
	v_permlane32_swap_b32_e32 v120, v121
	v_max3_f32 v120, v122, v120, v121
	v_add_f32_e32 v121, 0x41000000, v122
	v_cmp_gt_f32_e32 vcc, v120, v121
	s_cbranch_vccz .LBB0_169
	v_sub_f32_e32 v121, v122, v120
	v_exp_f32_e32 v122, v121
	s_nop 0
	v_mul_f32_e32 v96, v96, v122
	v_pk_mul_f32 v[14:15], v[14:15], v[122:123] op_sel_hi:[1,0]
	v_pk_mul_f32 v[12:13], v[12:13], v[122:123] op_sel_hi:[1,0]
	v_pk_mul_f32 v[10:11], v[10:11], v[122:123] op_sel_hi:[1,0]
	v_pk_mul_f32 v[8:9], v[8:9], v[122:123] op_sel_hi:[1,0]
	v_pk_mul_f32 v[6:7], v[6:7], v[122:123] op_sel_hi:[1,0]
	v_pk_mul_f32 v[4:5], v[4:5], v[122:123] op_sel_hi:[1,0]
	v_pk_mul_f32 v[2:3], v[2:3], v[122:123] op_sel_hi:[1,0]
	v_pk_mul_f32 v[0:1], v[0:1], v[122:123] op_sel_hi:[1,0]
	v_pk_mul_f32 v[30:31], v[30:31], v[122:123] op_sel_hi:[1,0]
	v_pk_mul_f32 v[28:29], v[28:29], v[122:123] op_sel_hi:[1,0]
	v_pk_mul_f32 v[26:27], v[26:27], v[122:123] op_sel_hi:[1,0]
	v_pk_mul_f32 v[24:25], v[24:25], v[122:123] op_sel_hi:[1,0]
	v_pk_mul_f32 v[22:23], v[22:23], v[122:123] op_sel_hi:[1,0]
	v_pk_mul_f32 v[20:21], v[20:21], v[122:123] op_sel_hi:[1,0]
	v_pk_mul_f32 v[18:19], v[18:19], v[122:123] op_sel_hi:[1,0]
	v_pk_mul_f32 v[16:17], v[16:17], v[122:123] op_sel_hi:[1,0]
	s_branch .LBB0_170

.LBB0_185:
	v_cndmask_b32_e64 v32, 0, 1, s[40:41]
	v_cmp_ne_u32_e64 s[0:1], 1, v32
	s_and_saveexec_b64 s[40:41], s[68:69]
	s_cbranch_execz .LBB0_192
	v_add_u32_e32 v40, v122, v116
	ds_read_b128 v[32:35], v40
	ds_read_b128 v[98:101], v40 offset:32
	ds_read_b128 v[36:39], v40 offset:4608
	ds_read_b128 v[102:105], v40 offset:4640
	ds_read_b128 v[106:109], v40 offset:64
	ds_read_b128 v[110:113], v40 offset:96
	ds_read_b128 v[126:129], v40 offset:4672
	ds_read_b128 v[130:133], v40 offset:4704
	s_setprio 1
	s_waitcnt lgkmcnt(7)
	v_mfma_f32_32x32x16_bf16 v[48:63], v[32:35], v[64:67], 0
	s_waitcnt lgkmcnt(5)
	v_mfma_f32_32x32x16_bf16 v[32:47], v[36:39], v[64:67], 0
	v_mfma_f32_32x32x16_bf16 v[48:63], v[98:101], v[68:71], v[48:63]
	s_waitcnt lgkmcnt(4)
	v_mfma_f32_32x32x16_bf16 v[32:47], v[102:105], v[68:71], v[32:47]
	s_waitcnt lgkmcnt(3)
	v_mfma_f32_32x32x16_bf16 v[48:63], v[106:109], v[72:75], v[48:63]
	s_waitcnt lgkmcnt(1)
	v_mfma_f32_32x32x16_bf16 v[32:47], v[126:129], v[72:75], v[32:47]
	v_add_u32_e32 v126, v123, v116
	v_mfma_f32_32x32x16_bf16 v[48:63], v[110:113], v[76:79], v[48:63]
	ds_read_b128 v[110:113], v126 offset:9216
	ds_read_b128 v[106:109], v126 offset:9248
	ds_read_b128 v[102:105], v126 offset:9280
	ds_read_b128 v[98:101], v126 offset:9312
	s_waitcnt lgkmcnt(4)
	v_mfma_f32_32x32x16_bf16 v[32:47], v[130:133], v[76:79], v[32:47]
	s_setprio 0
	s_and_b64 vcc, exec, s[0:1]
	s_cbranch_vccnz .LBB0_188
	s_add_i32 s10, s27, -1
	v_add_u32_e32 v156, s10, v124
	s_lshl_b32 s11, s27, 1
	s_add_i32 s11, s11, -1
	v_add_u32_e32 v96, 0x77, v156
	v_add_u32_e32 v127, 0x57, v156
	v_add_u32_e32 v128, 0x76, v156
	v_cmp_gt_u32_e64 s[4:5], s11, v96
	v_cmp_gt_u32_e64 s[6:7], s11, v127
	v_cmp_gt_u32_e64 s[8:9], s11, v128
	v_cndmask_b32_e64 v48, v212, v48, s[4:5]
	v_cndmask_b32_e64 v32, v212, v32, s[6:7]
	v_cndmask_b32_e64 v49, v212, v49, s[8:9]
	v_add_u32_e32 v96, 0x56, v156
	v_add_u32_e32 v127, 0x75, v156
	v_add_u32_e32 v128, 0x55, v156
	v_cmp_gt_u32_e64 s[4:5], s11, v96
	v_cmp_gt_u32_e64 s[6:7], s11, v127
	v_cmp_gt_u32_e64 s[8:9], s11, v128
	v_cndmask_b32_e64 v33, v212, v33, s[4:5]
	v_cndmask_b32_e64 v50, v212, v50, s[6:7]
	v_cndmask_b32_e64 v34, v212, v34, s[8:9]
	v_add_u32_e32 v96, 0x74, v156
	v_add_u32_e32 v127, 0x54, v156
	v_add_u32_e32 v128, 0x73, v156
	v_cmp_gt_u32_e64 s[4:5], s11, v96
	v_cmp_gt_u32_e64 s[6:7], s11, v127
	v_cmp_gt_u32_e64 s[8:9], s11, v128
	v_cndmask_b32_e64 v51, v212, v51, s[4:5]
	v_cndmask_b32_e64 v35, v212, v35, s[6:7]
	v_cndmask_b32_e64 v52, v212, v52, s[8:9]
	v_add_u32_e32 v96, 0x53, v156
	v_add_u32_e32 v127, 0x72, v156
	v_add_u32_e32 v128, 0x52, v156
	v_cmp_gt_u32_e64 s[4:5], s11, v96
	v_cmp_gt_u32_e64 s[6:7], s11, v127
	v_cmp_gt_u32_e64 s[8:9], s11, v128
	v_cndmask_b32_e64 v36, v212, v36, s[4:5]
	v_cndmask_b32_e64 v53, v212, v53, s[6:7]
	v_cndmask_b32_e64 v37, v212, v37, s[8:9]
	v_add_u32_e32 v96, 0x71, v156
	v_add_u32_e32 v127, 0x51, v156
	v_add_u32_e32 v128, 0x70, v156
	v_cmp_gt_u32_e64 s[4:5], s11, v96
	v_cmp_gt_u32_e64 s[6:7], s11, v127
	v_cmp_gt_u32_e64 s[8:9], s11, v128
	v_cndmask_b32_e64 v54, v212, v54, s[4:5]
	v_cndmask_b32_e64 v38, v212, v38, s[6:7]
	v_cndmask_b32_e64 v55, v212, v55, s[8:9]
	v_add_u32_e32 v96, 0x50, v156
	v_add_u32_e32 v127, 0x67, v156
	v_add_u32_e32 v128, 0x47, v156
	v_cmp_gt_u32_e64 s[4:5], s11, v96
	v_cmp_gt_u32_e64 s[6:7], s11, v127
	v_cmp_gt_u32_e64 s[8:9], s11, v128
	v_cndmask_b32_e64 v39, v212, v39, s[4:5]
	v_cndmask_b32_e64 v56, v212, v56, s[6:7]
	v_cndmask_b32_e64 v40, v212, v40, s[8:9]
	v_add_u32_e32 v96, 0x66, v156
	v_add_u32_e32 v127, 0x46, v156
	v_add_u32_e32 v128, 0x65, v156
	v_cmp_gt_u32_e64 s[4:5], s11, v96
	v_cmp_gt_u32_e64 s[6:7], s11, v127
	v_cmp_gt_u32_e64 s[8:9], s11, v128
	v_cndmask_b32_e64 v57, v212, v57, s[4:5]
	v_cndmask_b32_e64 v41, v212, v41, s[6:7]
	v_cndmask_b32_e64 v58, v212, v58, s[8:9]
	v_add_u32_e32 v96, 0x45, v156
	v_add_u32_e32 v127, 0x64, v156
	v_add_u32_e32 v128, 0x44, v156
	v_cmp_gt_u32_e64 s[4:5], s11, v96
	v_cmp_gt_u32_e64 s[6:7], s11, v127
	v_cmp_gt_u32_e64 s[8:9], s11, v128
	v_cndmask_b32_e64 v42, v212, v42, s[4:5]
	v_cndmask_b32_e64 v59, v212, v59, s[6:7]
	v_cndmask_b32_e64 v43, v212, v43, s[8:9]
	v_add_u32_e32 v96, 0x63, v156
	v_add_u32_e32 v127, 0x43, v156
	v_add_u32_e32 v128, 0x62, v156
	v_cmp_gt_u32_e64 s[4:5], s11, v96
	v_cmp_gt_u32_e64 s[6:7], s11, v127
	v_cmp_gt_u32_e64 s[8:9], s11, v128
	v_cndmask_b32_e64 v60, v212, v60, s[4:5]
	v_cndmask_b32_e64 v44, v212, v44, s[6:7]
	v_cndmask_b32_e64 v61, v212, v61, s[8:9]
	v_add_u32_e32 v96, 0x42, v156
	v_add_u32_e32 v127, 0x61, v156
	v_add_u32_e32 v128, 0x41, v156
	v_cmp_gt_u32_e64 s[4:5], s11, v96
	v_cmp_gt_u32_e64 s[6:7], s11, v127
	v_cmp_gt_u32_e64 s[8:9], s11, v128
	v_cndmask_b32_e64 v45, v212, v45, s[4:5]
	v_cndmask_b32_e64 v62, v212, v62, s[6:7]
	v_cndmask_b32_e64 v46, v212, v46, s[8:9]
	v_add_u32_e32 v96, 0x60, v156
	v_add_u32_e32 v127, 64, v156
	v_cmp_gt_u32_e64 s[4:5], s11, v96
	v_cmp_gt_u32_e64 s[6:7], s11, v127
	s_nop 0
	v_cndmask_b32_e64 v63, v212, v63, s[4:5]
	v_cndmask_b32_e64 v47, v212, v47, s[6:7]

.LBB0_202:
	v_add_u32_e32 v40, v122, v116
	ds_read_b128 v[32:35], v40 offset:18432
	ds_read_b128 v[98:101], v40 offset:18464
	ds_read_b128 v[36:39], v40 offset:23040
	ds_read_b128 v[102:105], v40 offset:23072
	ds_read_b128 v[106:109], v40 offset:18496
	ds_read_b128 v[110:113], v40 offset:18528
	ds_read_b128 v[126:129], v40 offset:23104
	ds_read_b128 v[130:133], v40 offset:23136
	s_setprio 1
	s_waitcnt lgkmcnt(7)
	v_mfma_f32_32x32x16_bf16 v[48:63], v[32:35], v[64:67], 0
	s_waitcnt lgkmcnt(5)
	v_mfma_f32_32x32x16_bf16 v[32:47], v[36:39], v[64:67], 0
	v_mfma_f32_32x32x16_bf16 v[48:63], v[98:101], v[68:71], v[48:63]
	s_waitcnt lgkmcnt(4)
	v_mfma_f32_32x32x16_bf16 v[32:47], v[102:105], v[68:71], v[32:47]
	s_waitcnt lgkmcnt(3)
	v_mfma_f32_32x32x16_bf16 v[48:63], v[106:109], v[72:75], v[48:63]
	s_waitcnt lgkmcnt(1)
	v_mfma_f32_32x32x16_bf16 v[32:47], v[126:129], v[72:75], v[32:47]
	v_add_u32_e32 v126, v123, v116
	v_mfma_f32_32x32x16_bf16 v[48:63], v[110:113], v[76:79], v[48:63]
	ds_read_b128 v[110:113], v126 offset:27648
	ds_read_b128 v[106:109], v126 offset:27680
	ds_read_b128 v[102:105], v126 offset:27712
	ds_read_b128 v[98:101], v126 offset:27744
	s_waitcnt lgkmcnt(4)
	v_mfma_f32_32x32x16_bf16 v[32:47], v[130:133], v[76:79], v[32:47]
	s_setprio 0
	s_and_b64 vcc, exec, s[0:1]
	s_cbranch_vccnz .LBB0_204
	s_add_i32 s10, s27, -1
	v_add_u32_e32 v156, s10, v124
	s_lshl_b32 s11, s27, 1
	s_add_i32 s11, s11, -1
	v_add_u32_e32 v96, 55, v156
	v_add_u32_e32 v127, 23, v156
	v_add_u32_e32 v128, 54, v156
	v_cmp_gt_u32_e64 s[4:5], s11, v96
	v_cmp_gt_u32_e64 s[6:7], s11, v127
	v_cmp_gt_u32_e64 s[8:9], s11, v128
	v_cndmask_b32_e64 v48, v212, v48, s[4:5]
	v_cndmask_b32_e64 v32, v212, v32, s[6:7]
	v_cndmask_b32_e64 v49, v212, v49, s[8:9]
	v_add_u32_e32 v96, 22, v156
	v_add_u32_e32 v127, 53, v156
	v_add_u32_e32 v128, 21, v156
	v_cmp_gt_u32_e64 s[4:5], s11, v96
	v_cmp_gt_u32_e64 s[6:7], s11, v127
	v_cmp_gt_u32_e64 s[8:9], s11, v128
	v_cndmask_b32_e64 v33, v212, v33, s[4:5]
	v_cndmask_b32_e64 v50, v212, v50, s[6:7]
	v_cndmask_b32_e64 v34, v212, v34, s[8:9]
	v_add_u32_e32 v96, 52, v156
	v_add_u32_e32 v127, 20, v156
	v_add_u32_e32 v128, 51, v156
	v_cmp_gt_u32_e64 s[4:5], s11, v96
	v_cmp_gt_u32_e64 s[6:7], s11, v127
	v_cmp_gt_u32_e64 s[8:9], s11, v128
	v_cndmask_b32_e64 v51, v212, v51, s[4:5]
	v_cndmask_b32_e64 v35, v212, v35, s[6:7]
	v_cndmask_b32_e64 v52, v212, v52, s[8:9]
	v_add_u32_e32 v96, 19, v156
	v_add_u32_e32 v127, 50, v156
	v_add_u32_e32 v128, 18, v156
	v_cmp_gt_u32_e64 s[4:5], s11, v96
	v_cmp_gt_u32_e64 s[6:7], s11, v127
	v_cmp_gt_u32_e64 s[8:9], s11, v128
	v_cndmask_b32_e64 v36, v212, v36, s[4:5]
	v_cndmask_b32_e64 v53, v212, v53, s[6:7]
	v_cndmask_b32_e64 v37, v212, v37, s[8:9]
	v_add_u32_e32 v96, 49, v156
	v_add_u32_e32 v127, 17, v156
	v_add_u32_e32 v128, 48, v156
	v_cmp_gt_u32_e64 s[4:5], s11, v96
	v_cmp_gt_u32_e64 s[6:7], s11, v127
	v_cmp_gt_u32_e64 s[8:9], s11, v128
	v_cndmask_b32_e64 v54, v212, v54, s[4:5]
	v_cndmask_b32_e64 v38, v212, v38, s[6:7]
	v_cndmask_b32_e64 v55, v212, v55, s[8:9]
	v_add_u32_e32 v96, 16, v156
	v_add_u32_e32 v127, 39, v156
	v_add_u32_e32 v128, 7, v156
	v_cmp_gt_u32_e64 s[4:5], s11, v96
	v_cmp_gt_u32_e64 s[6:7], s11, v127
	v_cmp_gt_u32_e64 s[8:9], s11, v128
	v_cndmask_b32_e64 v39, v212, v39, s[4:5]
	v_cndmask_b32_e64 v56, v212, v56, s[6:7]
	v_cndmask_b32_e64 v40, v212, v40, s[8:9]
	v_add_u32_e32 v96, 38, v156
	v_add_u32_e32 v127, 6, v156
	v_add_u32_e32 v128, 37, v156
	v_cmp_gt_u32_e64 s[4:5], s11, v96
	v_cmp_gt_u32_e64 s[6:7], s11, v127
	v_cmp_gt_u32_e64 s[8:9], s11, v128
	v_cndmask_b32_e64 v57, v212, v57, s[4:5]
	v_cndmask_b32_e64 v41, v212, v41, s[6:7]
	v_cndmask_b32_e64 v58, v212, v58, s[8:9]
	v_add_u32_e32 v96, 5, v156
	v_add_u32_e32 v127, 36, v156
	v_add_u32_e32 v128, 4, v156
	v_cmp_gt_u32_e64 s[4:5], s11, v96
	v_cmp_gt_u32_e64 s[6:7], s11, v127
	v_cmp_gt_u32_e64 s[8:9], s11, v128
	v_cndmask_b32_e64 v42, v212, v42, s[4:5]
	v_cndmask_b32_e64 v59, v212, v59, s[6:7]
	v_cndmask_b32_e64 v43, v212, v43, s[8:9]
	v_add_u32_e32 v96, 35, v156
	v_add_u32_e32 v127, 3, v156
	v_add_u32_e32 v128, 34, v156
	v_cmp_gt_u32_e64 s[4:5], s11, v96
	v_cmp_gt_u32_e64 s[6:7], s11, v127
	v_cmp_gt_u32_e64 s[8:9], s11, v128
	v_cndmask_b32_e64 v60, v212, v60, s[4:5]
	v_cndmask_b32_e64 v44, v212, v44, s[6:7]
	v_cndmask_b32_e64 v61, v212, v61, s[8:9]
	v_add_u32_e32 v96, 2, v156
	v_add_u32_e32 v127, 33, v156
	v_add_u32_e32 v128, 1, v156
	v_cmp_gt_u32_e64 s[4:5], s11, v96
	v_cmp_gt_u32_e64 s[6:7], s11, v127
	v_cmp_gt_u32_e64 s[8:9], s11, v128
	v_cndmask_b32_e64 v45, v212, v45, s[4:5]
	v_cndmask_b32_e64 v62, v212, v62, s[6:7]
	v_cndmask_b32_e64 v46, v212, v46, s[8:9]
	v_add_u32_e32 v96, 32, v156
	v_add_u32_e32 v127, 0, v156
	v_cmp_gt_u32_e64 s[4:5], s11, v96
	v_cmp_gt_u32_e64 s[6:7], s11, v127
	s_nop 0
	v_cndmask_b32_e64 v63, v212, v63, s[4:5]
	v_cndmask_b32_e64 v47, v212, v47, s[6:7]

.LBB0_242:
	ds_read_b128 v[64:67], v183
	ds_read_b128 v[146:149], v183 offset:32
	ds_read_b128 v[68:71], v183 offset:4608
	ds_read_b128 v[150:153], v183 offset:4640
	ds_read_b128 v[154:157], v183 offset:64
	ds_read_b128 v[158:161], v183 offset:96
	ds_read_b128 v[166:169], v183 offset:4672
	ds_read_b128 v[188:191], v183 offset:4704
	s_setprio 1
	s_waitcnt lgkmcnt(7)
	v_mfma_f32_32x32x16_bf16 v[80:95], v[64:67], v[98:101], 0
	s_waitcnt lgkmcnt(5)
	v_mfma_f32_32x32x16_bf16 v[64:79], v[68:71], v[98:101], 0
	v_mfma_f32_32x32x16_bf16 v[80:95], v[146:149], v[102:105], v[80:95]
	s_waitcnt lgkmcnt(4)
	v_mfma_f32_32x32x16_bf16 v[64:79], v[150:153], v[102:105], v[64:79]
	s_waitcnt lgkmcnt(3)
	v_mfma_f32_32x32x16_bf16 v[80:95], v[154:157], v[106:109], v[80:95]
	s_waitcnt lgkmcnt(1)
	v_mfma_f32_32x32x16_bf16 v[64:79], v[166:169], v[106:109], v[64:79]
	v_mfma_f32_32x32x16_bf16 v[80:95], v[158:161], v[110:113], v[80:95]
	ds_read_b128 v[158:161], v184 offset:18432
	ds_read_b128 v[154:157], v184 offset:18464
	ds_read_b128 v[150:153], v184 offset:18496
	ds_read_b128 v[146:149], v184 offset:18528
	s_waitcnt lgkmcnt(4)
	v_mfma_f32_32x32x16_bf16 v[64:79], v[188:191], v[110:113], v[64:79]
	s_setprio 0
	s_nop 11
	v_max3_f32 v96, v64, v65, v66
	v_max3_f32 v96, v96, v67, v68
	v_max3_f32 v96, v96, v69, v70
	v_max3_f32 v96, v96, v71, v72
	v_max3_f32 v96, v96, v73, v74
	v_max3_f32 v96, v96, v75, v76
	v_max3_f32 v96, v96, v77, v78
	v_max3_f32 v96, v96, v79, v80
	v_max3_f32 v96, v96, v81, v82
	v_max3_f32 v96, v96, v83, v84
	v_max3_f32 v96, v96, v85, v86
	v_max3_f32 v96, v96, v87, v88
	v_max3_f32 v96, v96, v89, v90
	v_max3_f32 v96, v96, v91, v92
	v_max3_f32 v96, v96, v93, v94
	v_max_f32_e32 v96, v96, v95
	v_mov_b32_e32 v162, v96
	s_nop 1
	v_permlane32_swap_b32_e32 v96, v162
	v_max3_f32 v186, v187, v96, v162
	v_add_f32_e32 v96, 0x41000000, v187
	v_cmp_gt_f32_e32 vcc, v186, v96
	s_cbranch_vccz .LBB0_244
	v_sub_f32_e32 v96, v187, v186
	v_exp_f32_e32 v96, v96
	s_nop 0
	v_mul_f32_e32 v185, v185, v96
	v_pk_mul_f32 v[62:63], v[62:63], v[96:97] op_sel_hi:[1,0]
	v_pk_mul_f32 v[60:61], v[60:61], v[96:97] op_sel_hi:[1,0]
	v_pk_mul_f32 v[58:59], v[58:59], v[96:97] op_sel_hi:[1,0]
	v_pk_mul_f32 v[56:57], v[56:57], v[96:97] op_sel_hi:[1,0]
	v_pk_mul_f32 v[54:55], v[54:55], v[96:97] op_sel_hi:[1,0]
	v_pk_mul_f32 v[52:53], v[52:53], v[96:97] op_sel_hi:[1,0]
	v_pk_mul_f32 v[50:51], v[50:51], v[96:97] op_sel_hi:[1,0]
	v_pk_mul_f32 v[48:49], v[48:49], v[96:97] op_sel_hi:[1,0]
	v_pk_mul_f32 v[46:47], v[46:47], v[96:97] op_sel_hi:[1,0]
	v_pk_mul_f32 v[44:45], v[44:45], v[96:97] op_sel_hi:[1,0]
	v_pk_mul_f32 v[42:43], v[42:43], v[96:97] op_sel_hi:[1,0]
	v_pk_mul_f32 v[40:41], v[40:41], v[96:97] op_sel_hi:[1,0]
	v_pk_mul_f32 v[38:39], v[38:39], v[96:97] op_sel_hi:[1,0]
	v_pk_mul_f32 v[36:37], v[36:37], v[96:97] op_sel_hi:[1,0]
	v_pk_mul_f32 v[34:35], v[34:35], v[96:97] op_sel_hi:[1,0]
	v_pk_mul_f32 v[32:33], v[32:33], v[96:97] op_sel_hi:[1,0]
	v_pk_mul_f32 v[30:31], v[30:31], v[96:97] op_sel_hi:[1,0]
	v_pk_mul_f32 v[28:29], v[28:29], v[96:97] op_sel_hi:[1,0]
	v_pk_mul_f32 v[26:27], v[26:27], v[96:97] op_sel_hi:[1,0]
	v_pk_mul_f32 v[24:25], v[24:25], v[96:97] op_sel_hi:[1,0]
	v_pk_mul_f32 v[22:23], v[22:23], v[96:97] op_sel_hi:[1,0]
	v_pk_mul_f32 v[20:21], v[20:21], v[96:97] op_sel_hi:[1,0]
	v_pk_mul_f32 v[18:19], v[18:19], v[96:97] op_sel_hi:[1,0]
	v_pk_mul_f32 v[16:17], v[16:17], v[96:97] op_sel_hi:[1,0]
	v_pk_mul_f32 v[14:15], v[14:15], v[96:97] op_sel_hi:[1,0]
	v_pk_mul_f32 v[12:13], v[12:13], v[96:97] op_sel_hi:[1,0]
	v_pk_mul_f32 v[10:11], v[10:11], v[96:97] op_sel_hi:[1,0]
	v_pk_mul_f32 v[8:9], v[8:9], v[96:97] op_sel_hi:[1,0]
	v_pk_mul_f32 v[6:7], v[6:7], v[96:97] op_sel_hi:[1,0]
	v_pk_mul_f32 v[4:5], v[4:5], v[96:97] op_sel_hi:[1,0]
	v_pk_mul_f32 v[2:3], v[2:3], v[96:97] op_sel_hi:[1,0]
	v_pk_mul_f32 v[0:1], v[0:1], v[96:97] op_sel_hi:[1,0]
	s_branch .LBB0_245

.LBB0_247:
	v_add_f32_e32 v64, v80, v64
	v_add_f32_e32 v64, 0, v64
	v_add_f32_e32 v65, v81, v65
	v_add_f32_e32 v64, v65, v64
	v_add_f32_e32 v65, v82, v66
	v_add_f32_e32 v64, v65, v64
	v_add_f32_e32 v65, v83, v67
	v_add_f32_e32 v64, v65, v64
	v_add_f32_e32 v65, v84, v68
	v_add_f32_e32 v64, v65, v64
	v_add_f32_e32 v65, v85, v69
	v_add_f32_e32 v64, v65, v64
	v_add_f32_e32 v65, v86, v70
	v_add_f32_e32 v64, v65, v64
	v_add_f32_e32 v65, v87, v71
	v_add_f32_e32 v64, v65, v64
	v_add_f32_e32 v65, v88, v72
	v_add_f32_e32 v64, v65, v64
	v_add_f32_e32 v65, v89, v73
	v_add_f32_e32 v64, v65, v64
	v_add_f32_e32 v65, v90, v74
	v_add_f32_e32 v64, v65, v64
	v_add_f32_e32 v65, v91, v75
	v_add_f32_e32 v64, v65, v64
	v_add_f32_e32 v65, v92, v76
	v_add_f32_e32 v64, v65, v64
	v_add_f32_e32 v65, v93, v77
	v_add_f32_e32 v64, v65, v64
	v_add_f32_e32 v65, v94, v78
	v_add_f32_e32 v64, v65, v64
	v_add_f32_e32 v65, v95, v79
	v_add_f32_e32 v64, v65, v64
	v_add_f32_e32 v96, v185, v64
	ds_read_b128 v[64:67], v183 offset:41472
	ds_read_b128 v[68:71], v183 offset:36864
	ds_read_b128 v[146:149], v183 offset:36896
	ds_read_b128 v[150:153], v183 offset:41504
	ds_read_b128 v[154:157], v183 offset:36928
	ds_read_b128 v[158:161], v183 offset:41536
	ds_read_b128 v[166:169], v183 offset:36960
	ds_read_b128 v[188:191], v183 offset:41568
	s_setprio 1
	s_waitcnt lgkmcnt(6)
	v_mfma_f32_32x32x16_bf16 v[80:95], v[68:71], v[98:101], 0
	v_mfma_f32_32x32x16_bf16 v[64:79], v[64:67], v[98:101], 0
	s_waitcnt lgkmcnt(5)
	v_mfma_f32_32x32x16_bf16 v[80:95], v[146:149], v[102:105], v[80:95]
	s_waitcnt lgkmcnt(4)
	v_mfma_f32_32x32x16_bf16 v[64:79], v[150:153], v[102:105], v[64:79]
	s_waitcnt lgkmcnt(3)
	v_mfma_f32_32x32x16_bf16 v[80:95], v[154:157], v[106:109], v[80:95]
	s_waitcnt lgkmcnt(2)
	v_mfma_f32_32x32x16_bf16 v[64:79], v[158:161], v[106:109], v[64:79]
	ds_read_b128 v[158:161], v184 offset:55296
	ds_read_b128 v[154:157], v184 offset:55328
	ds_read_b128 v[150:153], v184 offset:55360
	ds_read_b128 v[146:149], v184 offset:55392
	s_waitcnt lgkmcnt(5)
	v_mfma_f32_32x32x16_bf16 v[80:95], v[166:169], v[110:113], v[80:95]
	s_waitcnt lgkmcnt(4)
	v_mfma_f32_32x32x16_bf16 v[64:79], v[188:191], v[110:113], v[64:79]
	s_setprio 0
	s_nop 11
	v_max3_f32 v162, v64, v65, v66
	v_max3_f32 v162, v162, v67, v68
	v_max3_f32 v162, v162, v69, v70
	v_max3_f32 v162, v162, v71, v72
	v_max3_f32 v162, v162, v73, v74
	v_max3_f32 v162, v162, v75, v76
	v_max3_f32 v162, v162, v77, v78
	v_max3_f32 v162, v162, v79, v80
	v_max3_f32 v162, v162, v81, v82
	v_max3_f32 v162, v162, v83, v84
	v_max3_f32 v162, v162, v85, v86
	v_max3_f32 v162, v162, v87, v88
	v_max3_f32 v162, v162, v89, v90
	v_max3_f32 v162, v162, v91, v92
	v_max3_f32 v162, v162, v93, v94
	v_max_f32_e32 v162, v162, v95
	v_mov_b32_e32 v163, v162
	s_nop 1
	v_permlane32_swap_b32_e32 v162, v163
	v_max3_f32 v187, v186, v162, v163
	v_add_f32_e32 v162, 0x41000000, v186
	v_cmp_gt_f32_e32 vcc, v187, v162
	s_cbranch_vccz .LBB0_249
	v_sub_f32_e32 v162, v186, v187
	v_exp_f32_e32 v162, v162
	s_nop 0
	v_mul_f32_e32 v96, v96, v162
	v_pk_mul_f32 v[62:63], v[62:63], v[162:163] op_sel_hi:[1,0]
	v_pk_mul_f32 v[60:61], v[60:61], v[162:163] op_sel_hi:[1,0]
	v_pk_mul_f32 v[58:59], v[58:59], v[162:163] op_sel_hi:[1,0]
	v_pk_mul_f32 v[56:57], v[56:57], v[162:163] op_sel_hi:[1,0]
	v_pk_mul_f32 v[54:55], v[54:55], v[162:163] op_sel_hi:[1,0]
	v_pk_mul_f32 v[52:53], v[52:53], v[162:163] op_sel_hi:[1,0]
	v_pk_mul_f32 v[50:51], v[50:51], v[162:163] op_sel_hi:[1,0]
	v_pk_mul_f32 v[48:49], v[48:49], v[162:163] op_sel_hi:[1,0]
	v_pk_mul_f32 v[46:47], v[46:47], v[162:163] op_sel_hi:[1,0]
	v_pk_mul_f32 v[44:45], v[44:45], v[162:163] op_sel_hi:[1,0]
	v_pk_mul_f32 v[42:43], v[42:43], v[162:163] op_sel_hi:[1,0]
	v_pk_mul_f32 v[40:41], v[40:41], v[162:163] op_sel_hi:[1,0]
	v_pk_mul_f32 v[38:39], v[38:39], v[162:163] op_sel_hi:[1,0]
	v_pk_mul_f32 v[36:37], v[36:37], v[162:163] op_sel_hi:[1,0]
	v_pk_mul_f32 v[34:35], v[34:35], v[162:163] op_sel_hi:[1,0]
	v_pk_mul_f32 v[32:33], v[32:33], v[162:163] op_sel_hi:[1,0]
	v_pk_mul_f32 v[30:31], v[30:31], v[162:163] op_sel_hi:[1,0]
	v_pk_mul_f32 v[28:29], v[28:29], v[162:163] op_sel_hi:[1,0]
	v_pk_mul_f32 v[26:27], v[26:27], v[162:163] op_sel_hi:[1,0]
	v_pk_mul_f32 v[24:25], v[24:25], v[162:163] op_sel_hi:[1,0]
	v_pk_mul_f32 v[22:23], v[22:23], v[162:163] op_sel_hi:[1,0]
	v_pk_mul_f32 v[20:21], v[20:21], v[162:163] op_sel_hi:[1,0]
	v_pk_mul_f32 v[18:19], v[18:19], v[162:163] op_sel_hi:[1,0]
	v_pk_mul_f32 v[16:17], v[16:17], v[162:163] op_sel_hi:[1,0]
	v_pk_mul_f32 v[14:15], v[14:15], v[162:163] op_sel_hi:[1,0]
	v_pk_mul_f32 v[12:13], v[12:13], v[162:163] op_sel_hi:[1,0]
	v_pk_mul_f32 v[10:11], v[10:11], v[162:163] op_sel_hi:[1,0]
	v_pk_mul_f32 v[8:9], v[8:9], v[162:163] op_sel_hi:[1,0]
	v_pk_mul_f32 v[6:7], v[6:7], v[162:163] op_sel_hi:[1,0]
	v_pk_mul_f32 v[4:5], v[4:5], v[162:163] op_sel_hi:[1,0]
	v_pk_mul_f32 v[2:3], v[2:3], v[162:163] op_sel_hi:[1,0]
	v_pk_mul_f32 v[0:1], v[0:1], v[162:163] op_sel_hi:[1,0]
	s_branch .LBB0_250

.LBB0_275:
	ds_read_b128 v[64:67], v183
	ds_read_b128 v[146:149], v183 offset:32
	ds_read_b128 v[68:71], v183 offset:4608
	ds_read_b128 v[150:153], v183 offset:4640
	ds_read_b128 v[154:157], v183 offset:64
	ds_read_b128 v[158:161], v183 offset:96
	ds_read_b128 v[166:169], v183 offset:4672
	ds_read_b128 v[188:191], v183 offset:4704
	s_setprio 1
	s_waitcnt lgkmcnt(7)
	v_mfma_f32_32x32x16_bf16 v[80:95], v[64:67], v[98:101], 0
	s_waitcnt lgkmcnt(5)
	v_mfma_f32_32x32x16_bf16 v[64:79], v[68:71], v[98:101], 0
	v_mfma_f32_32x32x16_bf16 v[80:95], v[146:149], v[102:105], v[80:95]
	s_waitcnt lgkmcnt(4)
	v_mfma_f32_32x32x16_bf16 v[64:79], v[150:153], v[102:105], v[64:79]
	s_waitcnt lgkmcnt(3)
	v_mfma_f32_32x32x16_bf16 v[80:95], v[154:157], v[106:109], v[80:95]
	s_waitcnt lgkmcnt(1)
	v_mfma_f32_32x32x16_bf16 v[64:79], v[166:169], v[106:109], v[64:79]
	v_mfma_f32_32x32x16_bf16 v[80:95], v[158:161], v[110:113], v[80:95]
	ds_read_b128 v[158:161], v184 offset:18432
	ds_read_b128 v[154:157], v184 offset:18464
	ds_read_b128 v[150:153], v184 offset:18496
	ds_read_b128 v[146:149], v184 offset:18528
	s_waitcnt lgkmcnt(4)
	v_mfma_f32_32x32x16_bf16 v[64:79], v[188:191], v[110:113], v[64:79]
	s_setprio 0
	s_nop 11
	v_max3_f32 v96, v64, v65, v66
	v_max3_f32 v96, v96, v67, v68
	v_max3_f32 v96, v96, v69, v70
	v_max3_f32 v96, v96, v71, v72
	v_max3_f32 v96, v96, v73, v74
	v_max3_f32 v96, v96, v75, v76
	v_max3_f32 v96, v96, v77, v78
	v_max3_f32 v96, v96, v79, v80
	v_max3_f32 v96, v96, v81, v82
	v_max3_f32 v96, v96, v83, v84
	v_max3_f32 v96, v96, v85, v86
	v_max3_f32 v96, v96, v87, v88
	v_max3_f32 v96, v96, v89, v90
	v_max3_f32 v96, v96, v91, v92
	v_max3_f32 v96, v96, v93, v94
	v_max_f32_e32 v96, v96, v95
	v_mov_b32_e32 v162, v96
	s_nop 1
	v_permlane32_swap_b32_e32 v96, v162
	v_max3_f32 v187, v186, v96, v162
	v_add_f32_e32 v96, 0x41000000, v186
	v_cmp_gt_f32_e32 vcc, v187, v96
	s_cbranch_vccz .LBB0_277
	v_sub_f32_e32 v96, v186, v187
	v_exp_f32_e32 v96, v96
	s_nop 0
	v_mul_f32_e32 v185, v185, v96
	v_pk_mul_f32 v[62:63], v[62:63], v[96:97] op_sel_hi:[1,0]
	v_pk_mul_f32 v[60:61], v[60:61], v[96:97] op_sel_hi:[1,0]
	v_pk_mul_f32 v[58:59], v[58:59], v[96:97] op_sel_hi:[1,0]
	v_pk_mul_f32 v[56:57], v[56:57], v[96:97] op_sel_hi:[1,0]
	v_pk_mul_f32 v[54:55], v[54:55], v[96:97] op_sel_hi:[1,0]
	v_pk_mul_f32 v[52:53], v[52:53], v[96:97] op_sel_hi:[1,0]
	v_pk_mul_f32 v[50:51], v[50:51], v[96:97] op_sel_hi:[1,0]
	v_pk_mul_f32 v[48:49], v[48:49], v[96:97] op_sel_hi:[1,0]
	v_pk_mul_f32 v[46:47], v[46:47], v[96:97] op_sel_hi:[1,0]
	v_pk_mul_f32 v[44:45], v[44:45], v[96:97] op_sel_hi:[1,0]
	v_pk_mul_f32 v[42:43], v[42:43], v[96:97] op_sel_hi:[1,0]
	v_pk_mul_f32 v[40:41], v[40:41], v[96:97] op_sel_hi:[1,0]
	v_pk_mul_f32 v[38:39], v[38:39], v[96:97] op_sel_hi:[1,0]
	v_pk_mul_f32 v[36:37], v[36:37], v[96:97] op_sel_hi:[1,0]
	v_pk_mul_f32 v[34:35], v[34:35], v[96:97] op_sel_hi:[1,0]
	v_pk_mul_f32 v[32:33], v[32:33], v[96:97] op_sel_hi:[1,0]
	v_pk_mul_f32 v[30:31], v[30:31], v[96:97] op_sel_hi:[1,0]
	v_pk_mul_f32 v[28:29], v[28:29], v[96:97] op_sel_hi:[1,0]
	v_pk_mul_f32 v[26:27], v[26:27], v[96:97] op_sel_hi:[1,0]
	v_pk_mul_f32 v[24:25], v[24:25], v[96:97] op_sel_hi:[1,0]
	v_pk_mul_f32 v[22:23], v[22:23], v[96:97] op_sel_hi:[1,0]
	v_pk_mul_f32 v[20:21], v[20:21], v[96:97] op_sel_hi:[1,0]
	v_pk_mul_f32 v[18:19], v[18:19], v[96:97] op_sel_hi:[1,0]
	v_pk_mul_f32 v[16:17], v[16:17], v[96:97] op_sel_hi:[1,0]
	v_pk_mul_f32 v[14:15], v[14:15], v[96:97] op_sel_hi:[1,0]
	v_pk_mul_f32 v[12:13], v[12:13], v[96:97] op_sel_hi:[1,0]
	v_pk_mul_f32 v[10:11], v[10:11], v[96:97] op_sel_hi:[1,0]
	v_pk_mul_f32 v[8:9], v[8:9], v[96:97] op_sel_hi:[1,0]
	v_pk_mul_f32 v[6:7], v[6:7], v[96:97] op_sel_hi:[1,0]
	v_pk_mul_f32 v[4:5], v[4:5], v[96:97] op_sel_hi:[1,0]
	v_pk_mul_f32 v[2:3], v[2:3], v[96:97] op_sel_hi:[1,0]
	v_pk_mul_f32 v[0:1], v[0:1], v[96:97] op_sel_hi:[1,0]
	s_branch .LBB0_278

.LBB0_285:
	v_add_f32_e32 v64, v80, v64
	v_add_f32_e32 v64, 0, v64
	v_add_f32_e32 v65, v81, v65
	v_add_f32_e32 v64, v65, v64
	v_add_f32_e32 v65, v82, v66
	v_add_f32_e32 v64, v65, v64
	v_add_f32_e32 v65, v83, v67
	v_add_f32_e32 v64, v65, v64
	v_add_f32_e32 v65, v84, v68
	v_add_f32_e32 v64, v65, v64
	v_add_f32_e32 v65, v85, v69
	v_add_f32_e32 v64, v65, v64
	v_add_f32_e32 v65, v86, v70
	v_add_f32_e32 v64, v65, v64
	v_add_f32_e32 v65, v87, v71
	v_add_f32_e32 v64, v65, v64
	v_add_f32_e32 v65, v88, v72
	v_add_f32_e32 v64, v65, v64
	v_add_f32_e32 v65, v89, v73
	v_add_f32_e32 v64, v65, v64
	v_add_f32_e32 v65, v90, v74
	v_add_f32_e32 v64, v65, v64
	v_add_f32_e32 v65, v91, v75
	v_add_f32_e32 v64, v65, v64
	v_add_f32_e32 v65, v92, v76
	v_add_f32_e32 v64, v65, v64
	v_add_f32_e32 v65, v93, v77
	v_add_f32_e32 v64, v65, v64
	v_add_f32_e32 v65, v94, v78
	v_add_f32_e32 v64, v65, v64
	v_add_f32_e32 v65, v95, v79
	v_add_f32_e32 v64, v65, v64
	v_add_f32_e32 v185, v185, v64
	ds_read_b128 v[64:67], v183 offset:41472
	ds_read_b128 v[68:71], v183 offset:36864
	ds_read_b128 v[146:149], v183 offset:36896
	ds_read_b128 v[150:153], v183 offset:41504
	ds_read_b128 v[154:157], v183 offset:36928
	ds_read_b128 v[158:161], v183 offset:41536
	ds_read_b128 v[166:169], v183 offset:36960
	ds_read_b128 v[188:191], v183 offset:41568
	s_setprio 1
	s_waitcnt lgkmcnt(6)
	v_mfma_f32_32x32x16_bf16 v[80:95], v[68:71], v[98:101], 0
	v_mfma_f32_32x32x16_bf16 v[64:79], v[64:67], v[98:101], 0
	s_waitcnt lgkmcnt(5)
	v_mfma_f32_32x32x16_bf16 v[80:95], v[146:149], v[102:105], v[80:95]
	s_waitcnt lgkmcnt(4)
	v_mfma_f32_32x32x16_bf16 v[64:79], v[150:153], v[102:105], v[64:79]
	s_waitcnt lgkmcnt(3)
	v_mfma_f32_32x32x16_bf16 v[80:95], v[154:157], v[106:109], v[80:95]
	s_waitcnt lgkmcnt(2)
	v_mfma_f32_32x32x16_bf16 v[64:79], v[158:161], v[106:109], v[64:79]
	ds_read_b128 v[158:161], v184 offset:55296
	ds_read_b128 v[154:157], v184 offset:55328
	ds_read_b128 v[150:153], v184 offset:55360
	ds_read_b128 v[146:149], v184 offset:55392
	s_waitcnt lgkmcnt(5)
	v_mfma_f32_32x32x16_bf16 v[80:95], v[166:169], v[110:113], v[80:95]
	s_waitcnt lgkmcnt(4)
	v_mfma_f32_32x32x16_bf16 v[64:79], v[188:191], v[110:113], v[64:79]
	s_setprio 0
	s_nop 11
	v_max3_f32 v96, v64, v65, v66
	v_max3_f32 v96, v96, v67, v68
	v_max3_f32 v96, v96, v69, v70
	v_max3_f32 v96, v96, v71, v72
	v_max3_f32 v96, v96, v73, v74
	v_max3_f32 v96, v96, v75, v76
	v_max3_f32 v96, v96, v77, v78
	v_max3_f32 v96, v96, v79, v80
	v_max3_f32 v96, v96, v81, v82
	v_max3_f32 v96, v96, v83, v84
	v_max3_f32 v96, v96, v85, v86
	v_max3_f32 v96, v96, v87, v88
	v_max3_f32 v96, v96, v89, v90
	v_max3_f32 v96, v96, v91, v92
	v_max3_f32 v96, v96, v93, v94
	v_max_f32_e32 v96, v96, v95
	v_mov_b32_e32 v162, v96
	s_nop 1
	v_permlane32_swap_b32_e32 v96, v162
	v_max3_f32 v186, v187, v96, v162
	v_add_f32_e32 v96, 0x41000000, v187
	v_cmp_gt_f32_e32 vcc, v186, v96
	s_cbranch_vccz .LBB0_287
	v_sub_f32_e32 v96, v187, v186
	v_exp_f32_e32 v96, v96
	s_nop 0
	v_mul_f32_e32 v185, v185, v96
	v_pk_mul_f32 v[62:63], v[62:63], v[96:97] op_sel_hi:[1,0]
	v_pk_mul_f32 v[60:61], v[60:61], v[96:97] op_sel_hi:[1,0]
	v_pk_mul_f32 v[58:59], v[58:59], v[96:97] op_sel_hi:[1,0]
	v_pk_mul_f32 v[56:57], v[56:57], v[96:97] op_sel_hi:[1,0]
	v_pk_mul_f32 v[54:55], v[54:55], v[96:97] op_sel_hi:[1,0]
	v_pk_mul_f32 v[52:53], v[52:53], v[96:97] op_sel_hi:[1,0]
	v_pk_mul_f32 v[50:51], v[50:51], v[96:97] op_sel_hi:[1,0]
	v_pk_mul_f32 v[48:49], v[48:49], v[96:97] op_sel_hi:[1,0]
	v_pk_mul_f32 v[46:47], v[46:47], v[96:97] op_sel_hi:[1,0]
	v_pk_mul_f32 v[44:45], v[44:45], v[96:97] op_sel_hi:[1,0]
	v_pk_mul_f32 v[42:43], v[42:43], v[96:97] op_sel_hi:[1,0]
	v_pk_mul_f32 v[40:41], v[40:41], v[96:97] op_sel_hi:[1,0]
	v_pk_mul_f32 v[38:39], v[38:39], v[96:97] op_sel_hi:[1,0]
	v_pk_mul_f32 v[36:37], v[36:37], v[96:97] op_sel_hi:[1,0]
	v_pk_mul_f32 v[34:35], v[34:35], v[96:97] op_sel_hi:[1,0]
	v_pk_mul_f32 v[32:33], v[32:33], v[96:97] op_sel_hi:[1,0]
	v_pk_mul_f32 v[30:31], v[30:31], v[96:97] op_sel_hi:[1,0]
	v_pk_mul_f32 v[28:29], v[28:29], v[96:97] op_sel_hi:[1,0]
	v_pk_mul_f32 v[26:27], v[26:27], v[96:97] op_sel_hi:[1,0]
	v_pk_mul_f32 v[24:25], v[24:25], v[96:97] op_sel_hi:[1,0]
	v_pk_mul_f32 v[22:23], v[22:23], v[96:97] op_sel_hi:[1,0]
	v_pk_mul_f32 v[20:21], v[20:21], v[96:97] op_sel_hi:[1,0]
	v_pk_mul_f32 v[18:19], v[18:19], v[96:97] op_sel_hi:[1,0]
	v_pk_mul_f32 v[16:17], v[16:17], v[96:97] op_sel_hi:[1,0]
	v_pk_mul_f32 v[14:15], v[14:15], v[96:97] op_sel_hi:[1,0]
	v_pk_mul_f32 v[12:13], v[12:13], v[96:97] op_sel_hi:[1,0]
	v_pk_mul_f32 v[10:11], v[10:11], v[96:97] op_sel_hi:[1,0]
	v_pk_mul_f32 v[8:9], v[8:9], v[96:97] op_sel_hi:[1,0]
	v_pk_mul_f32 v[6:7], v[6:7], v[96:97] op_sel_hi:[1,0]
	v_pk_mul_f32 v[4:5], v[4:5], v[96:97] op_sel_hi:[1,0]
	v_pk_mul_f32 v[2:3], v[2:3], v[96:97] op_sel_hi:[1,0]
	v_pk_mul_f32 v[0:1], v[0:1], v[96:97] op_sel_hi:[1,0]
	s_branch .LBB0_288
